# DP: diff units process two adjacent 64-query blocks per K/V tile stream (even-qt units become no-ops), epilogue run twice
# baseline (speedup 1.0000x reference)
.LBB0_692:
	s_and_b64 vcc, exec, s[4:5]
	s_cbranch_vccz .LBB0_709
	s_sub_i32 s0, s13, 40
	s_lshr_b32 s7, s0, 3
	s_sub_i32 s4, 0x7f, s7
	s_and_b32 s1, s4, 1
	s_cmp_eq_u32 s1, 0
	s_cbranch_scc1 .Ldp_skip
	s_waitcnt vmcnt(1)
	v_mov_b32_e32 v12, v156
	s_lshl_b32 s0, s4, 6
	v_ashrrev_i32_e32 v142, 7, v12
	s_and_b32 s6, s13, 7
	v_and_b32_e32 v141, 31, v12
	v_lshl_add_u32 v13, v142, 5, s0
	v_or_b32_e32 v128, v13, v141
	s_lshl_b32 s5, s6, 20
	v_readlane_b32 s0, v234, 46
	v_readlane_b32 s1, v234, 47
	s_add_u32 s0, s0, s5
	v_ashrrev_i32_e32 v129, 31, v128
	v_bfe_u32 v143, v12, 6, 1
	s_addc_u32 s1, s1, 0
	v_lshlrev_b64 v[2:3], 7, v[128:129]
	v_bfe_u32 v140, v12, 5, 1
	v_lshl_add_u64 v[2:3], s[0:1], 0, v[2:3]
	v_lshlrev_b32_e32 v130, 6, v143
	v_mov_b32_e32 v131, v1
	v_lshl_add_u64 v[2:3], v[2:3], 0, v[130:131]
	v_lshlrev_b32_e32 v132, 4, v140
	v_mov_b32_e32 v133, v1
	v_lshl_add_u64 v[2:3], v[2:3], 0, v[132:133]
	global_load_dwordx4 v[96:99], v[2:3], off
	global_load_dwordx4 v[100:103], v[2:3], off offset:32
	s_mov_b32 s16, 0xffffe000
	s_mov_b32 s17, -1
	v_lshl_add_u64 v[226:227], v[2:3], 0, s[16:17]
	global_load_dwordx4 v[184:187], v[226:227], off
	global_load_dwordx4 v[188:191], v[226:227], off offset:32
	v_readlane_b32 s0, v234, 44
	v_ashrrev_i32_e32 v2, 3, v12
	v_readlane_b32 s1, v234, 45
	s_add_u32 s0, s0, s5
	v_lshlrev_b32_e32 v0, 3, v12
	v_ashrrev_i32_e32 v3, 31, v2
	s_addc_u32 s1, s1, 0
	v_readlane_b32 s8, v234, 42
	v_and_b32_e32 v0, 56, v0
	v_lshlrev_b64 v[4:5], 7, v[2:3]
	v_readlane_b32 s9, v234, 43
	s_add_u32 s8, s8, s5
	v_lshl_add_u64 v[4:5], s[0:1], 0, v[4:5]
	v_lshlrev_b32_e32 v0, 1, v0
	s_addc_u32 s9, s9, 0
	v_lshl_add_u64 v[6:7], v[4:5], 0, v[0:1]
	v_lshlrev_b64 v[4:5], 14, v[2:3]
	v_lshl_add_u64 v[4:5], s[8:9], 0, v[4:5]
	v_add_u32_e32 v3, 0x100, v12
	v_lshl_add_u64 v[134:135], v[4:5], 0, v[0:1]
	v_ashrrev_i32_e32 v4, 3, v3
	v_ashrrev_i32_e32 v5, 31, v4
	v_lshlrev_b64 v[10:11], 14, v[4:5]
	v_lshlrev_b64 v[8:9], 7, v[4:5]
	v_lshl_add_u64 v[10:11], s[8:9], 0, v[10:11]
	v_lshl_add_u64 v[8:9], s[0:1], 0, v[8:9]
	v_lshl_add_u64 v[136:137], v[10:11], 0, v[0:1]
	s_barrier
	global_load_dwordx4 v[104:107], v[134:135], off
	v_lshl_add_u64 v[8:9], v[8:9], 0, v[0:1]
	global_load_dwordx4 v[108:111], v[6:7], off
	global_load_dwordx4 v[112:115], v[8:9], off
	global_load_dwordx4 v[116:119], v[136:137], off
	v_lshlrev_b32_e32 v3, 4, v12
	s_movk_i32 s5, 0x90
	v_and_b32_e32 v131, 0x70, v3
	v_mul_lo_u32 v133, v2, s5
	s_movk_i32 s8, 0x88
	v_mul_lo_u32 v144, v2, s8
	v_add_u32_e32 v3, v131, v133
	v_mul_lo_u32 v145, v4, s5
	v_mul_lo_u32 v146, v4, s8
	v_readfirstlane_b32 s5, v13
	s_cmpk_eq_i32 s7, 0x7f
	v_add3_u32 v5, v131, v144, s33
	v_add_u32_e32 v10, v131, v145
	v_add3_u32 v11, v131, v146, s33
	s_waitcnt vmcnt(2)
	ds_write_b128 v3, v[108:111]
	ds_write2_b64 v5, v[104:105], v[106:107] offset1:1
	s_waitcnt vmcnt(1)
	ds_write_b128 v10, v[112:115]
	s_waitcnt vmcnt(0)
	ds_write2_b64 v11, v[116:117], v[118:119] offset1:1
	s_cbranch_scc1 .LBB0_695
	v_add_co_u32_e32 v6, vcc, 0x2000, v6
	s_nop 1
	v_addc_co_u32_e32 v7, vcc, 0, v7, vcc
	v_add_co_u32_e32 v8, vcc, 0x2000, v8
	s_nop 1
	v_addc_co_u32_e32 v9, vcc, 0, v9, vcc
	global_load_dwordx4 v[108:111], v[6:7], off
	global_load_dwordx4 v[112:115], v[8:9], off
	global_load_dwordx4 v[104:107], v[134:135], off offset:128
	global_load_dwordx4 v[116:119], v[136:137], off offset:128
.LBB0_695:
	v_mov_b32_e32 v14, v1
	v_mov_b32_e32 v15, v1
	v_lshl_add_u64 v[138:139], s[0:1], 0, v[0:1]
	v_add_u32_e32 v150, 0x80, v4
	v_add_u32_e32 v151, 0x80, v2
	v_mov_b32_e32 v0, v1
	v_mov_b32_e32 v2, v1
	v_mov_b32_e32 v3, v1
	v_mov_b32_e32 v4, v1
	v_mov_b32_e32 v5, v1
	v_mov_b32_e32 v6, v1
	v_mov_b32_e32 v7, v1
	v_mov_b32_e32 v8, v1
	v_mov_b32_e32 v9, v1
	v_mov_b32_e32 v10, v1
	v_mov_b32_e32 v11, v1
	v_mov_b32_e32 v12, v1
	v_mov_b32_e32 v13, v1
	v_mov_b32_e32 v48, 0x42000000
	v_mov_b64_e32 v[30:31], v[14:15]
	v_mov_b64_e32 v[46:47], v[14:15]
	v_lshlrev_b32_e32 v147, 3, v140
	s_or_b32 s5, s5, 31
	v_mul_u32_u24_e32 v148, 0x90, v141
	v_lshlrev_b32_e32 v125, 2, v140
	v_mul_u32_u24_e32 v149, 0x88, v141
	s_mov_b32 s7, 0
	v_mov_b32_e32 v153, 0xc2000000
	v_mov_b32_e32 v152, 0
	v_mov_b64_e32 v[28:29], v[12:13]
	v_mov_b64_e32 v[26:27], v[10:11]
	v_mov_b64_e32 v[24:25], v[8:9]
	v_mov_b64_e32 v[22:23], v[6:7]
	v_mov_b64_e32 v[20:21], v[4:5]
	v_mov_b64_e32 v[18:19], v[2:3]
	v_mov_b64_e32 v[16:17], v[0:1]
	v_mov_b64_e32 v[44:45], v[12:13]
	v_mov_b64_e32 v[42:43], v[10:11]
	v_mov_b64_e32 v[40:41], v[8:9]
	v_mov_b64_e32 v[38:39], v[6:7]
	v_mov_b64_e32 v[36:37], v[4:5]
	v_mov_b64_e32 v[34:35], v[2:3]
	v_mov_b64_e32 v[32:33], v[0:1]
	s_mov_b32 s0, 0
	s_mov_b32 s8, 0
	v_mov_b32_e32 v49, v48
	v_mov_b32_e32 v50, v48
	v_mov_b32_e32 v51, v48
	v_mov_b32_e32 v52, v48
	v_mov_b32_e32 v53, v48
	v_mov_b32_e32 v54, v48
	v_mov_b32_e32 v55, v48
	v_mov_b32_e32 v56, v48
	v_mov_b32_e32 v57, v48
	v_mov_b32_e32 v58, v48
	v_mov_b32_e32 v59, v48
	v_mov_b32_e32 v60, v48
	v_mov_b32_e32 v61, v48
	v_mov_b32_e32 v62, v48
	v_mov_b32_e32 v63, v48
	s_and_b32 s10, s13, 7
	s_lshl_b32 s10, s10, 20
	v_readlane_b32 s16, v234, 44
	v_readlane_b32 s17, v234, 45
	v_readlane_b32 s11, v234, 42
	v_readlane_b32 s12, v234, 43
	s_add_u32 s16, s16, s10
	s_addc_u32 s17, s17, 0
	s_add_u32 s10, s11, s10
	s_addc_u32 s11, s12, 0
	s_add_u32 s18, s16, 0x4000
	s_addc_u32 s12, s17, 0
	s_add_u32 s16, s10, 0x100
	s_addc_u32 s17, s11, 0
	s_mov_b32 s10, s18
	s_mov_b32 s11, s12
	v_lshlrev_b32_e32 v180, 4, v156
	v_lshrrev_b32_e32 v182, 3, v156
	v_and_b32_e32 v183, 7, v156
	v_add_u32_e32 v181, 0x1000, v180
	v_lshlrev_b32_e32 v182, 14, v182
	v_lshl_add_u32 v182, v183, 4, v182
	v_add_u32_e32 v183, 0x80000, v182
	v_mov_b32_e32 v192, v1
	v_mov_b32_e32 v193, v1
	v_mov_b32_e32 v194, v1
	v_mov_b32_e32 v195, v1
	v_mov_b32_e32 v196, v1
	v_mov_b32_e32 v197, v1
	v_mov_b32_e32 v198, v1
	v_mov_b32_e32 v199, v1
	v_mov_b32_e32 v200, v1
	v_mov_b32_e32 v201, v1
	v_mov_b32_e32 v202, v1
	v_mov_b32_e32 v203, v1
	v_mov_b32_e32 v204, v1
	v_mov_b32_e32 v205, v1
	v_mov_b32_e32 v206, v1
	v_mov_b32_e32 v207, v1
	v_mov_b32_e32 v208, v1
	v_mov_b32_e32 v209, v1
	v_mov_b32_e32 v210, v1
	v_mov_b32_e32 v211, v1
	v_mov_b32_e32 v212, v1
	v_mov_b32_e32 v213, v1
	v_mov_b32_e32 v214, v1
	v_mov_b32_e32 v215, v1
	v_mov_b32_e32 v216, v1
	v_mov_b32_e32 v217, v1
	v_mov_b32_e32 v218, v1
	v_mov_b32_e32 v219, v1
	v_mov_b32_e32 v220, v1
	v_mov_b32_e32 v221, v1
	v_mov_b32_e32 v222, v1
	v_mov_b32_e32 v223, v1
	v_mov_b32_e32 v224, v1
	v_add_u32_e32 v225, 0xffffffc0, v128
	s_mov_b32 s18, 1

.LBB0_705:
	s_nop 7
	v_exp_f32_e32 v2, v80
	v_exp_f32_e32 v3, v81
	v_exp_f32_e32 v4, v82
	v_exp_f32_e32 v5, v83
	v_add_f32_e32 v0, 0, v2
	v_exp_f32_e32 v6, v84
	v_add_f32_e32 v0, v3, v0
	v_exp_f32_e32 v7, v85
	v_add_f32_e32 v0, v4, v0
	v_exp_f32_e32 v8, v86
	v_add_f32_e32 v0, v5, v0
	v_exp_f32_e32 v9, v87
	v_add_f32_e32 v0, v6, v0
	v_add_f32_e32 v0, v7, v0
	v_add3_u32 v86, s14, v147, v149
	v_add_f32_e32 v0, v8, v0
	v_add_u32_e32 v87, 0x2000, v86
	v_add_f32_e32 v0, v9, v0
	v_cvt_pk_bf16_f32 v2, v2, v3
	v_cvt_pk_bf16_f32 v3, v4, v5
	v_cvt_pk_bf16_f32 v4, v6, v7
	v_cvt_pk_bf16_f32 v5, v8, v9
	ds_read2_b64 v[6:9], v87 offset0:128 offset1:130
	ds_read2_b64 v[10:13], v87 offset0:132 offset1:134
	v_add_u32_e32 v86, 0x3000, v86
	s_waitcnt lgkmcnt(1)
	v_mfma_f32_32x32x16_bf16 v[32:47], v[6:9], v[2:5], v[32:47]
	ds_read2_b64 v[6:9], v86 offset0:160 offset1:162
	v_exp_f32_e32 v14, v88
	v_exp_f32_e32 v15, v89
	v_exp_f32_e32 v80, v90
	v_exp_f32_e32 v81, v91
	v_exp_f32_e32 v82, v92
	v_exp_f32_e32 v83, v93
	s_waitcnt lgkmcnt(0)
	v_mfma_f32_32x32x16_bf16 v[16:31], v[6:9], v[2:5], v[16:31]
	ds_read2_b64 v[6:9], v86 offset0:164 offset1:166
	v_exp_f32_e32 v84, v94
	v_exp_f32_e32 v85, v95
	v_cvt_pk_bf16_f32 v2, v14, v15
	v_cvt_pk_bf16_f32 v3, v80, v81
	v_cvt_pk_bf16_f32 v4, v82, v83
	v_cvt_pk_bf16_f32 v5, v84, v85
	v_exp_f32_e32 v64, v64
	v_exp_f32_e32 v65, v65
	s_waitcnt lgkmcnt(0)
	v_mfma_f32_32x32x16_bf16 v[16:31], v[6:9], v[2:5], v[16:31]
	ds_read2_b64 v[6:9], v87 offset0:136 offset1:138
	v_exp_f32_e32 v66, v66
	v_exp_f32_e32 v67, v67
	v_exp_f32_e32 v68, v68
	v_exp_f32_e32 v69, v69
	v_exp_f32_e32 v70, v70
	v_exp_f32_e32 v71, v71
	v_mfma_f32_32x32x16_bf16 v[32:47], v[10:13], v[2:5], v[32:47]
	v_cvt_pk_bf16_f32 v2, v64, v65
	v_cvt_pk_bf16_f32 v3, v66, v67
	v_cvt_pk_bf16_f32 v4, v68, v69
	v_cvt_pk_bf16_f32 v5, v70, v71
	v_add_f32_e32 v0, v14, v0
	v_add_f32_e32 v0, v15, v0
	v_add_f32_e32 v0, v80, v0
	s_waitcnt lgkmcnt(0)
	v_mfma_f32_32x32x16_bf16 v[32:47], v[6:9], v[2:5], v[32:47]
	ds_read2_b64 v[6:9], v86 offset0:168 offset1:170
	v_add_f32_e32 v0, v81, v0
	v_exp_f32_e32 v72, v72
	v_exp_f32_e32 v73, v73
	v_exp_f32_e32 v74, v74
	v_exp_f32_e32 v75, v75
	v_exp_f32_e32 v76, v76
	s_waitcnt lgkmcnt(0)
	v_mfma_f32_32x32x16_bf16 v[16:31], v[6:9], v[2:5], v[16:31]
	ds_read2_b64 v[6:9], v87 offset0:140 offset1:142
	v_exp_f32_e32 v77, v77
	v_exp_f32_e32 v78, v78
	v_exp_f32_e32 v79, v79
	v_add_f32_e32 v0, v82, v0
	v_add_f32_e32 v0, v83, v0
	v_add_f32_e32 v0, v84, v0
	v_add_f32_e32 v0, v85, v0
	v_cvt_pk_bf16_f32 v2, v72, v73
	v_cvt_pk_bf16_f32 v3, v74, v75
	v_cvt_pk_bf16_f32 v4, v76, v77
	v_cvt_pk_bf16_f32 v5, v78, v79
	v_add_f32_e32 v0, v64, v0
	v_add_f32_e32 v0, v65, v0
	s_waitcnt lgkmcnt(0)
	v_mfma_f32_32x32x16_bf16 v[32:47], v[6:9], v[2:5], v[32:47]
	ds_read2_b64 v[6:9], v86 offset0:172 offset1:174
	v_add_f32_e32 v0, v66, v0
	v_add_f32_e32 v0, v67, v0
	v_add_f32_e32 v0, v68, v0
	v_add_f32_e32 v0, v69, v0
	v_add_f32_e32 v0, v70, v0
	v_add_f32_e32 v0, v71, v0
	v_add_f32_e32 v0, v72, v0
	v_add_f32_e32 v0, v73, v0
	s_waitcnt lgkmcnt(0)
	v_mfma_f32_32x32x16_bf16 v[16:31], v[6:9], v[2:5], v[16:31]
	v_add_f32_e32 v0, v74, v0
	v_add_f32_e32 v0, v75, v0
	v_add_f32_e32 v0, v76, v0
	v_add_f32_e32 v0, v77, v0
	v_add_f32_e32 v0, v78, v0
	v_add_f32_e32 v0, v79, v0
	v_add_f32_e32 v152, v152, v0
	v_cmp_lt_f32_e32 vcc, s20, v0
	s_cbranch_vccz .Ldp_A
	v_mov_b32_e32 v2, v0
	s_nop 1
	v_permlane32_swap_b32_e32 v0, v2
	v_add_f32_e32 v0, v0, v2
	v_log_f32_e32 v2, v0
	v_cmp_lt_f32_e32 vcc, s20, v0
	s_nop 1
	v_cndmask_b32_e32 v2, 0, v2, vcc
	v_exp_f32_e64 v0, -v2
	v_add_f32_e32 v153, v153, v2
	v_xor_b32_e32 v63, 0x80000000, v153
	v_mov_b32_e32 v62, v63
	v_mul_f32_e32 v152, v152, v0
	v_mul_f32_e32 v224, v224, v0
	v_pk_mul_f32 v[192:193], v[192:193], v[0:1] op_sel_hi:[1,0]
	v_pk_mul_f32 v[194:195], v[194:195], v[0:1] op_sel_hi:[1,0]
	v_pk_mul_f32 v[196:197], v[196:197], v[0:1] op_sel_hi:[1,0]
	v_pk_mul_f32 v[198:199], v[198:199], v[0:1] op_sel_hi:[1,0]
	v_pk_mul_f32 v[200:201], v[200:201], v[0:1] op_sel_hi:[1,0]
	v_pk_mul_f32 v[202:203], v[202:203], v[0:1] op_sel_hi:[1,0]
	v_pk_mul_f32 v[204:205], v[204:205], v[0:1] op_sel_hi:[1,0]
	v_pk_mul_f32 v[206:207], v[206:207], v[0:1] op_sel_hi:[1,0]
	v_pk_mul_f32 v[208:209], v[208:209], v[0:1] op_sel_hi:[1,0]
	v_pk_mul_f32 v[210:211], v[210:211], v[0:1] op_sel_hi:[1,0]
	v_pk_mul_f32 v[212:213], v[212:213], v[0:1] op_sel_hi:[1,0]
	v_pk_mul_f32 v[214:215], v[214:215], v[0:1] op_sel_hi:[1,0]
	v_pk_mul_f32 v[216:217], v[216:217], v[0:1] op_sel_hi:[1,0]
	v_pk_mul_f32 v[218:219], v[218:219], v[0:1] op_sel_hi:[1,0]
	v_pk_mul_f32 v[220:221], v[220:221], v[0:1] op_sel_hi:[1,0]
	v_pk_mul_f32 v[222:223], v[222:223], v[0:1] op_sel_hi:[1,0]
	v_pk_mul_f32 v[46:47], v[46:47], v[0:1] op_sel_hi:[1,0]
	v_pk_mul_f32 v[44:45], v[44:45], v[0:1] op_sel_hi:[1,0]
	v_pk_mul_f32 v[42:43], v[42:43], v[0:1] op_sel_hi:[1,0]
	v_pk_mul_f32 v[40:41], v[40:41], v[0:1] op_sel_hi:[1,0]
	v_pk_mul_f32 v[38:39], v[38:39], v[0:1] op_sel_hi:[1,0]
	v_pk_mul_f32 v[36:37], v[36:37], v[0:1] op_sel_hi:[1,0]
	v_pk_mul_f32 v[34:35], v[34:35], v[0:1] op_sel_hi:[1,0]
	v_pk_mul_f32 v[32:33], v[32:33], v[0:1] op_sel_hi:[1,0]
	v_pk_mul_f32 v[30:31], v[30:31], v[0:1] op_sel_hi:[1,0]
	v_pk_mul_f32 v[28:29], v[28:29], v[0:1] op_sel_hi:[1,0]
	v_pk_mul_f32 v[26:27], v[26:27], v[0:1] op_sel_hi:[1,0]
	v_pk_mul_f32 v[24:25], v[24:25], v[0:1] op_sel_hi:[1,0]
	v_pk_mul_f32 v[22:23], v[22:23], v[0:1] op_sel_hi:[1,0]
	v_pk_mul_f32 v[20:21], v[20:21], v[0:1] op_sel_hi:[1,0]
	v_pk_mul_f32 v[18:19], v[18:19], v[0:1] op_sel_hi:[1,0]
	v_pk_mul_f32 v[16:17], v[16:17], v[0:1] op_sel_hi:[1,0]
	v_mov_b32_e32 v61, v63
	v_mov_b32_e32 v60, v63
	v_mov_b32_e32 v59, v63
	v_mov_b32_e32 v58, v63
	v_mov_b32_e32 v57, v63
	v_mov_b32_e32 v56, v63
	v_mov_b32_e32 v55, v63
	v_mov_b32_e32 v54, v63
	v_mov_b32_e32 v53, v63
	v_mov_b32_e32 v52, v63
	v_mov_b32_e32 v51, v63
	v_mov_b32_e32 v50, v63
	v_mov_b32_e32 v49, v63
	v_mov_b32_e32 v48, v63
.Ldp_A:
	s_cmp_eq_u32 s8, s4
	s_cbranch_scc1 .LBB0_707
	v_add_u32_e32 v0, s14, v148
	v_add3_u32 v0, v0, v130, v132
	ds_read_b128 v[2:5], v0
	s_waitcnt lgkmcnt(0)
	v_mfma_f32_32x32x16_bf16 v[80:95], v[2:5], v[184:187], v[48:63]
	ds_read_b128 v[2:5], v0 offset:4608
	s_add_i32 s0, s7, 63
	v_cmp_le_i32_e32 vcc, s0, v225
	s_cmp_eq_u64 vcc, exec
	s_waitcnt lgkmcnt(0)
	v_mfma_f32_32x32x16_bf16 v[64:79], v[2:5], v[184:187], v[48:63]
	ds_read_b128 v[2:5], v0 offset:32
	s_waitcnt lgkmcnt(0)
	v_mfma_f32_32x32x16_bf16 v[80:95], v[2:5], v[188:191], v[80:95]
	ds_read_b128 v[2:5], v0 offset:4640
	s_waitcnt lgkmcnt(0)
	v_mfma_f32_32x32x16_bf16 v[64:79], v[2:5], v[188:191], v[64:79]
	s_cbranch_scc1 .Ldp_A705
	v_add_u32_e32 v0, s7, v125
	v_cmp_lt_i32_e32 vcc, v0, v225
	v_add_u32_e32 v2, 2, v0
	s_nop 4
	v_cndmask_b32_e32 v81, v169, v81, vcc
	v_cmp_le_i32_e32 vcc, v0, v225
	s_nop 1
	v_cndmask_b32_e32 v80, v169, v80, vcc
	v_cmp_le_i32_e32 vcc, v2, v225
	v_add_u32_e32 v2, 3, v0
	s_nop 0
	v_cndmask_b32_e32 v82, v169, v82, vcc
	v_cmp_le_i32_e32 vcc, v2, v225
	v_add_u32_e32 v2, 8, v0
	s_nop 0
	v_cndmask_b32_e32 v83, v169, v83, vcc
	v_cmp_le_i32_e32 vcc, v2, v225
	v_add_u32_e32 v2, 9, v0
	s_nop 0
	v_cndmask_b32_e32 v84, v169, v84, vcc
	v_cmp_le_i32_e32 vcc, v2, v225
	v_add_u32_e32 v2, 10, v0
	s_nop 0
	v_cndmask_b32_e32 v85, v169, v85, vcc
	v_cmp_le_i32_e32 vcc, v2, v225
	v_add_u32_e32 v2, 11, v0
	s_nop 0
	v_cndmask_b32_e32 v86, v169, v86, vcc
	v_cmp_le_i32_e32 vcc, v2, v225
	v_add_u32_e32 v2, 16, v0
	s_nop 0
	v_cndmask_b32_e32 v87, v169, v87, vcc
	v_cmp_le_i32_e32 vcc, v2, v225
	v_add_u32_e32 v2, 17, v0
	s_nop 0
	v_cndmask_b32_e32 v88, v169, v88, vcc
	v_cmp_le_i32_e32 vcc, v2, v225
	v_add_u32_e32 v2, 18, v0
	s_nop 0
	v_cndmask_b32_e32 v89, v169, v89, vcc
	v_cmp_le_i32_e32 vcc, v2, v225
	v_add_u32_e32 v2, 19, v0
	s_nop 0
	v_cndmask_b32_e32 v90, v169, v90, vcc
	v_cmp_le_i32_e32 vcc, v2, v225
	v_add_u32_e32 v2, 24, v0
	s_nop 0
	v_cndmask_b32_e32 v91, v169, v91, vcc
	v_cmp_le_i32_e32 vcc, v2, v225
	v_add_u32_e32 v2, 25, v0
	s_nop 0
	v_cndmask_b32_e32 v92, v169, v92, vcc
	v_cmp_le_i32_e32 vcc, v2, v225
	v_add_u32_e32 v2, 26, v0
	s_nop 0
	v_cndmask_b32_e32 v93, v169, v93, vcc
	v_cmp_le_i32_e32 vcc, v2, v225
	v_add_u32_e32 v2, 27, v0
	s_nop 0
	v_cndmask_b32_e32 v94, v169, v94, vcc
	v_cmp_le_i32_e32 vcc, v2, v225
	v_add_u32_e32 v2, 32, v0
	s_nop 0
	v_cndmask_b32_e32 v95, v169, v95, vcc
	v_cmp_le_i32_e32 vcc, v2, v225
	v_add_u32_e32 v2, 33, v0
	s_nop 0
	v_cndmask_b32_e32 v64, v169, v64, vcc
	v_cmp_le_i32_e32 vcc, v2, v225
	v_add_u32_e32 v2, 34, v0
	s_nop 0
	v_cndmask_b32_e32 v65, v169, v65, vcc
	v_cmp_le_i32_e32 vcc, v2, v225
	v_add_u32_e32 v2, 35, v0
	s_nop 0
	v_cndmask_b32_e32 v66, v169, v66, vcc
	v_cmp_le_i32_e32 vcc, v2, v225
	v_add_u32_e32 v2, 40, v0
	s_nop 0
	v_cndmask_b32_e32 v67, v169, v67, vcc
	v_cmp_le_i32_e32 vcc, v2, v225
	v_add_u32_e32 v2, 41, v0
	s_nop 0
	v_cndmask_b32_e32 v68, v169, v68, vcc
	v_cmp_le_i32_e32 vcc, v2, v225
	v_add_u32_e32 v2, 42, v0
	s_nop 0
	v_cndmask_b32_e32 v69, v169, v69, vcc
	v_cmp_le_i32_e32 vcc, v2, v225
	v_add_u32_e32 v2, 43, v0
	s_nop 0
	v_cndmask_b32_e32 v70, v169, v70, vcc
	v_cmp_le_i32_e32 vcc, v2, v225
	v_add_u32_e32 v2, 48, v0
	s_nop 0
	v_cndmask_b32_e32 v71, v169, v71, vcc
	v_cmp_le_i32_e32 vcc, v2, v225
	v_add_u32_e32 v2, 49, v0
	s_nop 0
	v_cndmask_b32_e32 v72, v169, v72, vcc
	v_cmp_le_i32_e32 vcc, v2, v225
	v_add_u32_e32 v2, 50, v0
	s_nop 0
	v_cndmask_b32_e32 v73, v169, v73, vcc
	v_cmp_le_i32_e32 vcc, v2, v225
	v_add_u32_e32 v2, 51, v0
	s_nop 0
	v_cndmask_b32_e32 v74, v169, v74, vcc
	v_cmp_le_i32_e32 vcc, v2, v225
	v_add_u32_e32 v2, 56, v0
	s_nop 0
	v_cndmask_b32_e32 v75, v169, v75, vcc
	v_cmp_le_i32_e32 vcc, v2, v225
	v_add_u32_e32 v2, 57, v0
	s_nop 0
	v_cndmask_b32_e32 v76, v169, v76, vcc
	v_cmp_le_i32_e32 vcc, v2, v225
	v_add_u32_e32 v2, 58, v0
	v_add_u32_e32 v0, 59, v0
	v_cndmask_b32_e32 v77, v169, v77, vcc
	v_cmp_le_i32_e32 vcc, v2, v225
	s_nop 1
	v_cndmask_b32_e32 v78, v169, v78, vcc
	v_cmp_gt_i32_e32 vcc, v0, v225
	s_and_saveexec_b64 s[0:1], vcc
	v_mov_b32_e32 v79, 0xf149f2ca
	s_or_b64 exec, exec, s[0:1]
.Ldp_A705:
	s_nop 7
	v_exp_f32_e32 v2, v80
	v_exp_f32_e32 v3, v81
	v_exp_f32_e32 v4, v82
	v_exp_f32_e32 v5, v83
	v_add_f32_e32 v0, 0, v2
	v_exp_f32_e32 v6, v84
	v_add_f32_e32 v0, v3, v0
	v_exp_f32_e32 v7, v85
	v_add_f32_e32 v0, v4, v0
	v_exp_f32_e32 v8, v86
	v_add_f32_e32 v0, v5, v0
	v_exp_f32_e32 v9, v87
	v_add_f32_e32 v0, v6, v0
	v_add_f32_e32 v0, v7, v0
	v_add3_u32 v86, s14, v147, v149
	v_add_f32_e32 v0, v8, v0
	v_add_u32_e32 v87, 0x2000, v86
	v_add_f32_e32 v0, v9, v0
	v_cvt_pk_bf16_f32 v2, v2, v3
	v_cvt_pk_bf16_f32 v3, v4, v5
	v_cvt_pk_bf16_f32 v4, v6, v7
	v_cvt_pk_bf16_f32 v5, v8, v9
	ds_read2_b64 v[6:9], v87 offset0:128 offset1:130
	ds_read2_b64 v[10:13], v87 offset0:132 offset1:134
	v_add_u32_e32 v86, 0x3000, v86
	s_waitcnt lgkmcnt(1)
	v_mfma_f32_32x32x16_bf16 v[192:207], v[6:9], v[2:5], v[192:207]
	ds_read2_b64 v[6:9], v86 offset0:160 offset1:162
	v_exp_f32_e32 v14, v88
	v_exp_f32_e32 v15, v89
	v_exp_f32_e32 v80, v90
	v_exp_f32_e32 v81, v91
	v_exp_f32_e32 v82, v92
	v_exp_f32_e32 v83, v93
	s_waitcnt lgkmcnt(0)
	v_mfma_f32_32x32x16_bf16 v[208:223], v[6:9], v[2:5], v[208:223]
	ds_read2_b64 v[6:9], v86 offset0:164 offset1:166
	v_exp_f32_e32 v84, v94
	v_exp_f32_e32 v85, v95
	v_cvt_pk_bf16_f32 v2, v14, v15
	v_cvt_pk_bf16_f32 v3, v80, v81
	v_cvt_pk_bf16_f32 v4, v82, v83
	v_cvt_pk_bf16_f32 v5, v84, v85
	v_exp_f32_e32 v64, v64
	v_exp_f32_e32 v65, v65
	s_waitcnt lgkmcnt(0)
	v_mfma_f32_32x32x16_bf16 v[208:223], v[6:9], v[2:5], v[208:223]
	ds_read2_b64 v[6:9], v87 offset0:136 offset1:138
	v_exp_f32_e32 v66, v66
	v_exp_f32_e32 v67, v67
	v_exp_f32_e32 v68, v68
	v_exp_f32_e32 v69, v69
	v_exp_f32_e32 v70, v70
	v_exp_f32_e32 v71, v71
	v_mfma_f32_32x32x16_bf16 v[192:207], v[10:13], v[2:5], v[192:207]
	v_cvt_pk_bf16_f32 v2, v64, v65
	v_cvt_pk_bf16_f32 v3, v66, v67
	v_cvt_pk_bf16_f32 v4, v68, v69
	v_cvt_pk_bf16_f32 v5, v70, v71
	v_add_f32_e32 v0, v14, v0
	v_add_f32_e32 v0, v15, v0
	v_add_f32_e32 v0, v80, v0
	s_waitcnt lgkmcnt(0)
	v_mfma_f32_32x32x16_bf16 v[192:207], v[6:9], v[2:5], v[192:207]
	ds_read2_b64 v[6:9], v86 offset0:168 offset1:170
	v_add_f32_e32 v0, v81, v0
	v_exp_f32_e32 v72, v72
	v_exp_f32_e32 v73, v73
	v_exp_f32_e32 v74, v74
	v_exp_f32_e32 v75, v75
	v_exp_f32_e32 v76, v76
	s_waitcnt lgkmcnt(0)
	v_mfma_f32_32x32x16_bf16 v[208:223], v[6:9], v[2:5], v[208:223]
	ds_read2_b64 v[6:9], v87 offset0:140 offset1:142
	v_exp_f32_e32 v77, v77
	v_exp_f32_e32 v78, v78
	v_exp_f32_e32 v79, v79
	v_add_f32_e32 v0, v82, v0
	v_add_f32_e32 v0, v83, v0
	v_add_f32_e32 v0, v84, v0
	v_add_f32_e32 v0, v85, v0
	v_cvt_pk_bf16_f32 v2, v72, v73
	v_cvt_pk_bf16_f32 v3, v74, v75
	v_cvt_pk_bf16_f32 v4, v76, v77
	v_cvt_pk_bf16_f32 v5, v78, v79
	v_add_f32_e32 v0, v64, v0
	v_add_f32_e32 v0, v65, v0
	s_waitcnt lgkmcnt(0)
	v_mfma_f32_32x32x16_bf16 v[192:207], v[6:9], v[2:5], v[192:207]
	ds_read2_b64 v[6:9], v86 offset0:172 offset1:174
	v_add_f32_e32 v0, v66, v0
	v_add_f32_e32 v0, v67, v0
	v_add_f32_e32 v0, v68, v0
	v_add_f32_e32 v0, v69, v0
	v_add_f32_e32 v0, v70, v0
	v_add_f32_e32 v0, v71, v0
	v_add_f32_e32 v0, v72, v0
	v_add_f32_e32 v0, v73, v0
	s_waitcnt lgkmcnt(0)
	v_mfma_f32_32x32x16_bf16 v[208:223], v[6:9], v[2:5], v[208:223]
	v_add_f32_e32 v0, v74, v0
	v_add_f32_e32 v0, v75, v0
	v_add_f32_e32 v0, v76, v0
	v_add_f32_e32 v0, v77, v0
	v_add_f32_e32 v0, v78, v0
	v_add_f32_e32 v0, v79, v0
	v_add_f32_e32 v224, v224, v0
	v_cmp_lt_f32_e32 vcc, s20, v0
	s_cbranch_vccz .LBB0_707
	v_mov_b32_e32 v2, v0
	s_nop 1
	v_permlane32_swap_b32_e32 v0, v2
	v_add_f32_e32 v0, v0, v2
	v_log_f32_e32 v2, v0
	v_cmp_lt_f32_e32 vcc, s20, v0
	s_nop 1
	v_cndmask_b32_e32 v2, 0, v2, vcc
	v_exp_f32_e64 v0, -v2
	v_add_f32_e32 v153, v153, v2
	v_xor_b32_e32 v63, 0x80000000, v153
	v_mov_b32_e32 v62, v63
	v_mul_f32_e32 v224, v224, v0
	v_mul_f32_e32 v152, v152, v0
	v_pk_mul_f32 v[16:17], v[16:17], v[0:1] op_sel_hi:[1,0]
	v_pk_mul_f32 v[18:19], v[18:19], v[0:1] op_sel_hi:[1,0]
	v_pk_mul_f32 v[20:21], v[20:21], v[0:1] op_sel_hi:[1,0]
	v_pk_mul_f32 v[22:23], v[22:23], v[0:1] op_sel_hi:[1,0]
	v_pk_mul_f32 v[24:25], v[24:25], v[0:1] op_sel_hi:[1,0]
	v_pk_mul_f32 v[26:27], v[26:27], v[0:1] op_sel_hi:[1,0]
	v_pk_mul_f32 v[28:29], v[28:29], v[0:1] op_sel_hi:[1,0]
	v_pk_mul_f32 v[30:31], v[30:31], v[0:1] op_sel_hi:[1,0]
	v_pk_mul_f32 v[32:33], v[32:33], v[0:1] op_sel_hi:[1,0]
	v_pk_mul_f32 v[34:35], v[34:35], v[0:1] op_sel_hi:[1,0]
	v_pk_mul_f32 v[36:37], v[36:37], v[0:1] op_sel_hi:[1,0]
	v_pk_mul_f32 v[38:39], v[38:39], v[0:1] op_sel_hi:[1,0]
	v_pk_mul_f32 v[40:41], v[40:41], v[0:1] op_sel_hi:[1,0]
	v_pk_mul_f32 v[42:43], v[42:43], v[0:1] op_sel_hi:[1,0]
	v_pk_mul_f32 v[44:45], v[44:45], v[0:1] op_sel_hi:[1,0]
	v_pk_mul_f32 v[46:47], v[46:47], v[0:1] op_sel_hi:[1,0]
	v_pk_mul_f32 v[206:207], v[206:207], v[0:1] op_sel_hi:[1,0]
	v_pk_mul_f32 v[204:205], v[204:205], v[0:1] op_sel_hi:[1,0]
	v_pk_mul_f32 v[202:203], v[202:203], v[0:1] op_sel_hi:[1,0]
	v_pk_mul_f32 v[200:201], v[200:201], v[0:1] op_sel_hi:[1,0]
	v_pk_mul_f32 v[198:199], v[198:199], v[0:1] op_sel_hi:[1,0]
	v_pk_mul_f32 v[196:197], v[196:197], v[0:1] op_sel_hi:[1,0]
	v_pk_mul_f32 v[194:195], v[194:195], v[0:1] op_sel_hi:[1,0]
	v_pk_mul_f32 v[192:193], v[192:193], v[0:1] op_sel_hi:[1,0]
	v_pk_mul_f32 v[222:223], v[222:223], v[0:1] op_sel_hi:[1,0]
	v_pk_mul_f32 v[220:221], v[220:221], v[0:1] op_sel_hi:[1,0]
	v_pk_mul_f32 v[218:219], v[218:219], v[0:1] op_sel_hi:[1,0]
	v_pk_mul_f32 v[216:217], v[216:217], v[0:1] op_sel_hi:[1,0]
	v_pk_mul_f32 v[214:215], v[214:215], v[0:1] op_sel_hi:[1,0]
	v_pk_mul_f32 v[212:213], v[212:213], v[0:1] op_sel_hi:[1,0]
	v_pk_mul_f32 v[210:211], v[210:211], v[0:1] op_sel_hi:[1,0]
	v_pk_mul_f32 v[208:209], v[208:209], v[0:1] op_sel_hi:[1,0]
	v_mov_b32_e32 v61, v63
	v_mov_b32_e32 v60, v63
	v_mov_b32_e32 v59, v63
	v_mov_b32_e32 v58, v63
	v_mov_b32_e32 v57, v63
	v_mov_b32_e32 v56, v63
	v_mov_b32_e32 v55, v63
	v_mov_b32_e32 v54, v63
	v_mov_b32_e32 v53, v63
	v_mov_b32_e32 v52, v63
	v_mov_b32_e32 v51, v63
	v_mov_b32_e32 v50, v63
	v_mov_b32_e32 v49, v63
	v_mov_b32_e32 v48, v63

.LBB0_726:
	s_or_b64 exec, exec, s[0:1]
	s_cmp_eq_u32 s18, 0
	s_cbranch_scc1 .Ldp_epi_done
	s_mov_b32 s18, 0
	v_mov_b32_e32 v128, v225
	v_mov_b32_e32 v129, v1
	v_mov_b32_e32 v16, v208
	v_mov_b32_e32 v17, v209
	v_mov_b32_e32 v18, v210
	v_mov_b32_e32 v19, v211
	v_mov_b32_e32 v20, v212
	v_mov_b32_e32 v21, v213
	v_mov_b32_e32 v22, v214
	v_mov_b32_e32 v23, v215
	v_mov_b32_e32 v24, v216
	v_mov_b32_e32 v25, v217
	v_mov_b32_e32 v26, v218
	v_mov_b32_e32 v27, v219
	v_mov_b32_e32 v28, v220
	v_mov_b32_e32 v29, v221
	v_mov_b32_e32 v30, v222
	v_mov_b32_e32 v31, v223
	v_mov_b32_e32 v32, v192
	v_mov_b32_e32 v33, v193
	v_mov_b32_e32 v34, v194
	v_mov_b32_e32 v35, v195
	v_mov_b32_e32 v36, v196
	v_mov_b32_e32 v37, v197
	v_mov_b32_e32 v38, v198
	v_mov_b32_e32 v39, v199
	v_mov_b32_e32 v40, v200
	v_mov_b32_e32 v41, v201
	v_mov_b32_e32 v42, v202
	v_mov_b32_e32 v43, v203
	v_mov_b32_e32 v44, v204
	v_mov_b32_e32 v45, v205
	v_mov_b32_e32 v46, v206
	v_mov_b32_e32 v47, v207
	v_mov_b32_e32 v152, v224
	s_branch .LBB0_722
.Ldp_epi_done:
	s_mov_b64 s[72:73], s[84:85]
	s_cbranch_execnz .LBB0_638
	s_branch .LBB0_711
.Ldp_skip:
	s_mov_b64 s[72:73], s[84:85]
	s_branch .LBB0_638
